# ret_m1: key rows of token blocks 1-3 prefetched with block 0's loads (three serialized HBM round trips removed per item)
# baseline (speedup 1.0000x reference)
; #define LAS __attribute__((address_space(3)))
; __device__ __forceinline__ void ld8bf(const bf16_t* p, float (&o)[8]) { unpack8(*(const u32x4*)p, o); }
; __device__ __forceinline__ float ret_lg(int h) { return log1pf(-exp2f(-5.0f - (float)h)); }
; __device__ __forceinline__ void w_ret_m1(unsigned char* ws, const bf16_t* proj, LAS unsigned char* wl, int b, int ck_, int h, int lane) {
;     LAS bf16_t* vT = (LAS bf16_t*)wl; LAS bf16_t* kT = (LAS bf16_t*)(wl + TILE_B);
;     const int row0 = b * SEQ + 64 * ck_, lo = lane & 15, fq = lane >> 4; const float lg = ret_lg(h);
;     const float* cosT = (const float*)(ws + WS_ROPE); const float* sinT = cosT + SEQ * 32;
; #pragma unroll
;     for (int i = 0; i < 4; ++i) { const int m = (lane >> 2) + 16 * i, cp = lane & 3; float x1[8], x2[8];
;         const bf16_t* src = proj + (size_t)(row0 + m) * NIN + C_RK + 64 * h; ld8bf(src + 8 * cp, x1); ld8bf(src + 32 + 8 * cp, x2);
;         const float* cp_ = cosT + (64 * ck_ + m) * 32 + 8 * cp; const float* sp_ = sinT + (64 * ck_ + m) * 32 + 8 * cp;
;         const float sc = 0.125f * __expf((float)(63 - m) * lg);
.LBB0_516:
	s_lshr_b32 s21, s20, 8
	s_lshr_b32 s24, s20, 9
	s_add_i32 s21, s21, s20
	s_and_b32 s24, s24, 12
	s_add_i32 s21, s21, s24
	s_and_b32 s24, s21, 12
	s_cmp_lg_u32 s24, 8
	s_cbranch_scc1 .LBB0_515
	s_and_b32 s34, s21, 11
	s_ashr_i32 s21, s20, 31
	s_ashr_i32 s24, s20, 4
	s_lshr_b32 s21, s21, 25
	s_add_i32 s34, s34, -8
	s_add_i32 s27, s24, s21
	v_cvt_f32_u32_e32 v0, s34
	s_ashr_i32 s21, s27, 7
	s_and_b32 s27, s27, 0xffffff80
	s_sub_i32 s27, s24, s27
	s_lshl_b32 s24, s21, 13
	s_lshl_b32 s38, s27, 6
	s_add_i32 s35, s38, s24
	v_sub_f32_e32 v0, 0xc0a00000, v0
	s_mov_b32 s24, 0xc2fc0000
	v_cmp_gt_f32_e32 vcc, s24, v0
	s_and_b64 s[40:41], vcc, exec
	s_cselect_b32 s24, 0xffffffc0, 0
	v_cndmask_b32_e32 v1, 0, v204, vcc
	v_add_f32_e32 v0, v0, v1
	v_exp_f32_e32 v0, v0
	v_mov_b32_e32 v25, v144
	v_mov_b64_e32 v[22:23], s[8:9]
	v_ldexp_f32 v2, v0, s24
	v_sub_f32_e32 v4, 1.0, v2
	v_add_f32_e32 v0, -1.0, v4
	v_sub_f32_e32 v1, v0, v4
	v_add_f32_e32 v1, 1.0, v1
	v_sub_f32_e64 v0, -v2, v0
	v_add_f32_e32 v5, v0, v1
	v_frexp_mant_f32_e32 v0, v4
	v_cmp_gt_f32_e32 vcc, s77, v0
	v_cvt_f64_f32_e32 v[0:1], v4
	v_frexp_exp_i32_f64_e32 v0, v[0:1]
	v_subbrev_co_u32_e32 v10, vcc, 0, v0, vcc
	v_sub_u32_e32 v0, 0, v10
	v_ldexp_f32 v1, v4, v0
	v_add_f32_e32 v4, -1.0, v1
	v_add_f32_e32 v6, 1.0, v1
	v_ldexp_f32 v0, v5, v0
	v_add_f32_e32 v5, 1.0, v4
	v_add_f32_e32 v7, -1.0, v6
	v_sub_f32_e32 v5, v1, v5
	v_sub_f32_e32 v1, v1, v7
	v_add_f32_e32 v5, v0, v5
	v_add_f32_e32 v0, v0, v1
	v_add_f32_e32 v11, v6, v0
	v_rcp_f32_e32 v13, v11
	v_sub_f32_e32 v1, v11, v6
	v_sub_f32_e32 v12, v0, v1
	v_add_f32_e32 v1, v4, v5
	v_mul_f32_e32 v15, v1, v13
	v_sub_f32_e32 v0, v1, v4
	v_mul_f32_e32 v4, v11, v15
	v_fma_f32 v6, v15, v11, -v4
	v_fmac_f32_e32 v6, v15, v12
	v_sub_f32_e32 v14, v5, v0
	v_add_f32_e32 v0, v4, v6
	v_sub_f32_e32 v5, v1, v0
	v_pk_add_f32 v[8:9], v[0:1], v[4:5] neg_lo:[0,1] neg_hi:[0,1]
	v_mov_b32_e32 v7, v0
	v_pk_add_f32 v[0:1], v[8:9], v[6:7] neg_lo:[0,1] neg_hi:[0,1]
	v_cmp_nlt_f32_e32 vcc, 1.0, v2
	v_add_f32_e32 v1, v14, v1
	v_add_f32_e32 v0, v0, v1
	v_add_f32_e32 v1, v5, v0
	v_mul_f32_e32 v14, v13, v1
	v_mul_f32_e32 v4, v11, v14
	v_fma_f32 v6, v14, v11, -v4
	v_fmac_f32_e32 v6, v14, v12
	v_sub_f32_e32 v5, v5, v1
	v_add_f32_e32 v11, v0, v5
	v_add_f32_e32 v0, v4, v6
	v_sub_f32_e32 v5, v1, v0
	v_pk_add_f32 v[8:9], v[0:1], v[4:5] neg_lo:[0,1] neg_hi:[0,1]
	v_mov_b32_e32 v7, v0
	v_pk_add_f32 v[0:1], v[8:9], v[6:7] neg_lo:[0,1] neg_hi:[0,1]
	v_ashrrev_i32_e32 v36, 2, v25
	v_add_f32_e32 v1, v11, v1
	v_add_f32_e32 v0, v0, v1
	v_add_f32_e32 v1, v15, v14
	v_add_f32_e32 v0, v5, v0
	v_sub_f32_e32 v4, v1, v15
	v_mul_f32_e32 v0, v13, v0
	v_sub_f32_e32 v4, v14, v4
	v_add_f32_e32 v4, v4, v0
	v_add_f32_e32 v6, v1, v4
	v_mul_f32_e32 v7, v6, v6
	v_fmamk_f32 v0, v7, 0x3e9b6dac, v201
	v_fmaak_f32 v169, v7, v0, 0x3f2aaada
	v_cvt_f32_i32_e32 v0, v10
	v_sub_f32_e32 v1, v6, v1
	v_sub_f32_e32 v1, v4, v1
	v_ldexp_f32 v8, v1, 1
	v_mul_f32_e32 v1, v6, v7
	v_ldexp_f32 v5, v6, 1
	v_pk_mul_f32 v[6:7], v[0:1], v[168:169]
	s_lshl_b32 s24, s34, 7
	v_fma_f32 v4, v0, s94, -v6
	v_fmac_f32_e32 v4, 0xb102e308, v0
	v_pk_add_f32 v[0:1], v[6:7], v[4:5]
	s_nop 0
	v_sub_f32_e32 v5, v1, v5
	v_sub_f32_e32 v5, v7, v5
	v_add_f32_e32 v9, v8, v5
	v_mov_b32_e32 v8, v6
	v_pk_add_f32 v[6:7], v[0:1], v[6:7] neg_lo:[0,1] neg_hi:[0,1]
	v_pk_add_f32 v[10:11], v[0:1], v[8:9]
	v_mov_b32_e32 v5, v0
	v_mov_b32_e32 v7, v11
	v_pk_add_f32 v[12:13], v[4:5], v[6:7] neg_lo:[0,1] neg_hi:[0,1]
	v_pk_add_f32 v[4:5], v[4:5], v[6:7]
	v_mov_b32_e32 v16, v1
	v_pk_add_f32 v[6:7], v[4:5], v[0:1] op_sel:[1,0] op_sel_hi:[0,1] neg_lo:[0,1] neg_hi:[0,1]
	v_pk_add_f32 v[14:15], v[10:11], v[6:7] op_sel_hi:[1,0] neg_lo:[0,1] neg_hi:[0,1]
	v_mov_b32_e32 v10, v11
	v_mov_b32_e32 v11, v5
	v_mov_b32_e32 v17, v6
	v_pk_add_f32 v[6:7], v[10:11], v[16:17] neg_lo:[0,1] neg_hi:[0,1]
	v_mov_b32_e32 v8, v9
	v_mov_b32_e32 v9, v0
	v_pk_add_f32 v[0:1], v[8:9], v[6:7] neg_lo:[0,1] neg_hi:[0,1]
	v_mov_b32_e32 v14, v12
	v_pk_add_f32 v[6:7], v[14:15], v[0:1]
	v_mov_b32_e32 v13, v5
	v_pk_add_f32 v[8:9], v[6:7], v[6:7] op_sel:[0,1] op_sel_hi:[1,0]
	s_nop 0
	v_pk_add_f32 v[4:5], v[4:5], v[8:9] op_sel:[1,0] op_sel_hi:[0,1]
	v_mov_b32_e32 v7, v4
	v_pk_add_f32 v[10:11], v[6:7], v[12:13] neg_lo:[0,1] neg_hi:[0,1]
	v_mov_b32_e32 v1, v8
	v_sub_f32_e32 v5, v6, v10
	v_pk_add_f32 v[0:1], v[0:1], v[10:11] neg_lo:[0,1] neg_hi:[0,1]
	v_sub_f32_e32 v5, v12, v5
	v_add_f32_e32 v0, v0, v5
	v_add_f32_e32 v0, v0, v1
	v_add_f32_e32 v0, v4, v0
	v_cndmask_b32_e32 v0, v205, v0, vcc
	v_cmp_neq_f32_e32 vcc, 1.0, v2
	v_add_lshl_u32 v12, v36, s38, 5
	v_ashrrev_i32_e32 v13, 31, v12
	v_cndmask_b32_e32 v0, v206, v0, vcc
	v_cmp_gt_f32_e32 vcc, s95, v2
	v_lshlrev_b64 v[12:13], 2, v[12:13]
	s_nop 0
	v_cndmask_b32_e64 v35, v0, -v2, vcc
	v_lshlrev_b32_e32 v0, 3, v25
	v_and_b32_e32 v34, 24, v0
	v_lshlrev_b32_e32 v2, 2, v34
	v_lshl_add_u64 v[0:1], s[4:5], 0, v[2:3]
	v_lshl_add_u64 v[20:21], s[82:83], 0, v[2:3]
	v_lshl_add_u64 v[18:19], v[0:1], 0, v[12:13]
	v_lshl_add_u64 v[16:17], v[20:21], 0, v[12:13]
	v_sub_u32_e32 v12, 63, v36
	v_cvt_f32_i32_e32 v12, v12
	v_add_u32_e32 v2, s35, v36
	v_mad_i64_i32 v[4:5], s[40:41], v2, s72, v[22:23]
	v_mul_f32_e32 v12, v35, v12
	v_mul_f32_e32 v12, 0x3fb8aa3b, v12
	v_exp_f32_e32 v12, v12
	v_lshl_add_u64 v[4:5], v[4:5], 0, s[24:25]
	v_lshlrev_b32_e32 v2, 1, v34
	v_lshl_add_u64 v[4:5], v[4:5], 0, v[2:3]
	v_mov_b32_e32 v124, 0x18000
	v_mov_b32_e32 v125, 0
	v_lshl_add_u64 v[126:127], v[4:5], 0, v[124:125]
	global_load_dwordx4 v[8:11], v[4:5], off offset:2560
	s_nop 0
	global_load_dwordx4 v[4:7], v[4:5], off offset:2624
	v_mul_f32_e32 v24, 0x3e000000, v12
	global_load_dwordx4 v[12:15], v[18:19], off
	global_load_dwordx4 v[28:31], v[16:17], off
	global_load_dwordx4 v[178:181], v[18:19], off offset:16
	global_load_dwordx4 v[182:185], v[16:17], off offset:16
	global_load_dwordx4 v[100:103], v[126:127], off offset:2560
	global_load_dwordx4 v[104:107], v[126:127], off offset:2624
	v_lshl_add_u64 v[126:127], v[126:127], 0, v[124:125]
	global_load_dwordx4 v[108:111], v[126:127], off offset:2560
	global_load_dwordx4 v[112:115], v[126:127], off offset:2624
	v_lshl_add_u64 v[126:127], v[126:127], 0, v[124:125]
	global_load_dwordx4 v[116:119], v[126:127], off offset:2560
	global_load_dwordx4 v[120:123], v[126:127], off offset:2624
	s_waitcnt vmcnt(0) lgkmcnt(0)
; #define LAS __attribute__((address_space(3)))
; __device__ __forceinline__ u32x4 pack8(const float (&v)[8]) { u32x4 w; w.x = pk2(v[0], v[1]); w.y = pk2(v[2], v[3]); w.z = pk2(v[4], v[5]); w.w = pk2(v[6], v[7]); return w; }
; __device__ __forceinline__ void ld8bf(const bf16_t* p, float (&o)[8]) { unpack8(*(const u32x4*)p, o); }
; __device__ __forceinline__ void w_ret_m1(unsigned char* ws, const bf16_t* proj, LAS unsigned char* wl, int b, int ck_, int h, int lane) {
;     ...
;     for (int i = 0; i < 4; ++i) { const int m = (lane >> 2) + 16 * i, cp = lane & 3; float x1[8], x2[8];
;         const bf16_t* src = proj + (size_t)(row0 + m) * NIN + C_RK + 64 * h; ld8bf(src + 8 * cp, x1); ld8bf(src + 32 + 8 * cp, x2);
;         const float* cp_ = cosT + (64 * ck_ + m) * 32 + 8 * cp; const float* sp_ = sinT + (64 * ck_ + m) * 32 + 8 * cp;
;         const float sc = 0.125f * __expf((float)(63 - m) * lg);
;         float o1[8], o2[8];
; #pragma unroll
;         for (int j = 0; j < 8; ++j) { const float cs = cp_[j], sn = sp_[j]; o1[j] = (x1[j] * cs - x2[j] * sn) * sc; o2[j] = (x2[j] * cs + x1[j] * sn) * sc; }
;         *(LAS u32x4*)(kT + m * LD + 8 * cp) = pack8(o1); *(LAS u32x4*)(kT + m * LD + 32 + 8 * cp) = pack8(o2); }
	v_lshlrev_b32_e32 v32, 16, v8
	v_and_b32_e32 v33, 0xffff0000, v8
	v_lshlrev_b32_e32 v38, 16, v4
	v_and_b32_e32 v39, 0xffff0000, v4
	v_pk_mul_f32 v[26:27], v[28:29], v[32:33]
	v_pk_mul_f32 v[28:29], v[28:29], v[38:39]
	v_pk_fma_f32 v[26:27], v[12:13], v[38:39], v[26:27]
	v_pk_fma_f32 v[12:13], v[12:13], v[32:33], v[28:29] neg_lo:[0,0,1] neg_hi:[0,0,1]
	v_lshlrev_b32_e32 v8, 16, v9
	v_and_b32_e32 v9, 0xffff0000, v9
	v_pk_mul_f32 v[28:29], v[24:25], v[12:13] op_sel_hi:[0,1]
	v_lshlrev_b32_e32 v12, 16, v5
	v_and_b32_e32 v13, 0xffff0000, v5
	v_pk_mul_f32 v[4:5], v[30:31], v[8:9]
	v_lshlrev_b32_e32 v32, 16, v6
	v_pk_fma_f32 v[4:5], v[14:15], v[12:13], v[4:5]
	v_pk_mul_f32 v[12:13], v[30:31], v[12:13]
	v_lshlrev_b32_e32 v30, 16, v10
	v_pk_fma_f32 v[8:9], v[14:15], v[8:9], v[12:13] neg_lo:[0,0,1] neg_hi:[0,0,1]
	v_mov_b64_e32 v[12:13], v[178:179]
	v_mov_b64_e32 v[14:15], v[180:181]
	s_nop 0
	v_mov_b64_e32 v[16:17], v[182:183]
	v_mov_b64_e32 v[18:19], v[184:185]
	v_and_b32_e32 v31, 0xffff0000, v10
	v_and_b32_e32 v33, 0xffff0000, v6
	v_lshlrev_b32_e32 v10, 16, v11
	v_and_b32_e32 v11, 0xffff0000, v11
	v_lshlrev_b32_e32 v6, 16, v7
	v_and_b32_e32 v7, 0xffff0000, v7
	v_pk_mul_f32 v[8:9], v[24:25], v[8:9] op_sel_hi:[0,1]
	v_pk_mul_f32 v[4:5], v[24:25], v[4:5] op_sel_hi:[0,1]
	v_pk_mul_f32 v[26:27], v[24:25], v[26:27] op_sel_hi:[0,1]
	s_waitcnt vmcnt(0) lgkmcnt(0)
	v_pk_mul_f32 v[38:39], v[16:17], v[30:31]
	v_pk_mul_f32 v[16:17], v[16:17], v[32:33]
	v_pk_fma_f32 v[38:39], v[12:13], v[32:33], v[38:39]
	v_pk_fma_f32 v[12:13], v[12:13], v[30:31], v[16:17] neg_lo:[0,0,1] neg_hi:[0,0,1]
	v_pk_mul_f32 v[16:17], v[18:19], v[10:11]
	v_pk_mul_f32 v[12:13], v[24:25], v[12:13] op_sel_hi:[0,1]
	v_pk_fma_f32 v[16:17], v[14:15], v[6:7], v[16:17]
	v_pk_mul_f32 v[6:7], v[18:19], v[6:7]
	v_pk_mul_f32 v[38:39], v[24:25], v[38:39] op_sel_hi:[0,1]
	v_pk_fma_f32 v[6:7], v[14:15], v[10:11], v[6:7] neg_lo:[0,0,1] neg_hi:[0,0,1]
	v_pk_mul_f32 v[16:17], v[24:25], v[16:17] op_sel_hi:[0,1]
	v_pk_mul_f32 v[10:11], v[24:25], v[6:7] op_sel_hi:[0,1]
	v_cvt_pk_bf16_f32 v7, v8, v9
	v_cvt_pk_bf16_f32 v9, v10, v11
	v_mul_lo_u32 v10, v36, s23
	v_cvt_pk_bf16_f32 v6, v28, v29
	v_cvt_pk_bf16_f32 v8, v12, v13
	v_add3_u32 v18, s6, v10, v2
	v_add_u32_e32 v12, 16, v36
	ds_write_b128 v18, v[6:9] offset:9216
	v_cvt_pk_bf16_f32 v7, v4, v5
	v_add_u32_e32 v4, s35, v12
	v_mad_i64_i32 v[4:5], s[40:41], v4, s72, v[22:23]
	v_add_lshl_u32 v12, v12, s38, 5
	v_cvt_pk_bf16_f32 v6, v26, v27
	v_cvt_pk_bf16_f32 v8, v38, v39
	v_cvt_pk_bf16_f32 v9, v16, v17
	v_lshl_add_u64 v[4:5], v[4:5], 0, s[24:25]
	v_ashrrev_i32_e32 v13, 31, v12
	ds_write_b128 v18, v[6:9] offset:9280
	v_lshl_add_u64 v[4:5], v[4:5], 0, v[2:3]
	v_lshlrev_b64 v[12:13], 2, v[12:13]
	v_mov_b64_e32 v[8:9], v[100:101]
	v_mov_b64_e32 v[10:11], v[102:103]
	s_nop 0
	v_mov_b64_e32 v[4:5], v[104:105]
	v_mov_b64_e32 v[6:7], v[106:107]
	v_lshl_add_u64 v[38:39], v[0:1], 0, v[12:13]
	v_lshl_add_u64 v[40:41], v[20:21], 0, v[12:13]
	global_load_dwordx4 v[26:29], v[38:39], off
	global_load_dwordx4 v[30:33], v[40:41], off
	global_load_dwordx4 v[178:181], v[38:39], off offset:16
	global_load_dwordx4 v[182:185], v[40:41], off offset:16
	v_sub_u32_e32 v12, 47, v36
	v_cvt_f32_i32_e32 v12, v12
	v_mul_f32_e32 v12, v35, v12
	v_mul_f32_e32 v12, 0x3fb8aa3b, v12
	v_exp_f32_e32 v12, v12
	s_waitcnt vmcnt(0) lgkmcnt(0)
	v_lshlrev_b32_e32 v16, 16, v8
	v_and_b32_e32 v17, 0xffff0000, v8
	v_lshlrev_b32_e32 v42, 16, v4
	v_and_b32_e32 v43, 0xffff0000, v4
	v_pk_mul_f32 v[14:15], v[30:31], v[16:17]
	v_pk_mul_f32 v[30:31], v[30:31], v[42:43]
	v_lshlrev_b32_e32 v8, 16, v9
	v_and_b32_e32 v9, 0xffff0000, v9
	v_pk_fma_f32 v[14:15], v[26:27], v[42:43], v[14:15]
	v_pk_fma_f32 v[16:17], v[26:27], v[16:17], v[30:31] neg_lo:[0,0,1] neg_hi:[0,0,1]
	v_lshlrev_b32_e32 v26, 16, v5
	v_and_b32_e32 v27, 0xffff0000, v5
	v_pk_mul_f32 v[4:5], v[32:33], v[8:9]
	v_lshlrev_b32_e32 v42, 16, v10
	v_pk_fma_f32 v[4:5], v[28:29], v[26:27], v[4:5]
	v_pk_mul_f32 v[26:27], v[32:33], v[26:27]
	v_and_b32_e32 v43, 0xffff0000, v10
	v_pk_fma_f32 v[8:9], v[28:29], v[8:9], v[26:27] neg_lo:[0,0,1] neg_hi:[0,0,1]
	v_mov_b64_e32 v[26:27], v[178:179]
	v_mov_b64_e32 v[28:29], v[180:181]
	v_mov_b64_e32 v[30:31], v[182:183]
	v_mov_b64_e32 v[32:33], v[184:185]
	v_lshlrev_b32_e32 v44, 16, v6
	v_and_b32_e32 v45, 0xffff0000, v6
	v_lshlrev_b32_e32 v10, 16, v11
	v_and_b32_e32 v11, 0xffff0000, v11
	v_lshlrev_b32_e32 v6, 16, v7
	v_and_b32_e32 v7, 0xffff0000, v7
	v_mul_f32_e32 v12, 0x3e000000, v12
	v_pk_mul_f32 v[16:17], v[12:13], v[16:17] op_sel_hi:[0,1]
	v_pk_mul_f32 v[8:9], v[12:13], v[8:9] op_sel_hi:[0,1]
	v_pk_mul_f32 v[14:15], v[12:13], v[14:15] op_sel_hi:[0,1]
	v_pk_mul_f32 v[4:5], v[12:13], v[4:5] op_sel_hi:[0,1]
	s_waitcnt vmcnt(0) lgkmcnt(0)
; #define LAS __attribute__((address_space(3)))
; __device__ __forceinline__ u32x4 pack8(const float (&v)[8]) { u32x4 w; w.x = pk2(v[0], v[1]); w.y = pk2(v[2], v[3]); w.z = pk2(v[4], v[5]); w.w = pk2(v[6], v[7]); return w; }
; __device__ __forceinline__ void ld8bf(const bf16_t* p, float (&o)[8]) { unpack8(*(const u32x4*)p, o); }
; __device__ __forceinline__ void w_ret_m1(unsigned char* ws, const bf16_t* proj, LAS unsigned char* wl, int b, int ck_, int h, int lane) {
;     ...
;     for (int i = 0; i < 4; ++i) { const int m = (lane >> 2) + 16 * i, cp = lane & 3; float x1[8], x2[8];
;         const bf16_t* src = proj + (size_t)(row0 + m) * NIN + C_RK + 64 * h; ld8bf(src + 8 * cp, x1); ld8bf(src + 32 + 8 * cp, x2);
;         const float* cp_ = cosT + (64 * ck_ + m) * 32 + 8 * cp; const float* sp_ = sinT + (64 * ck_ + m) * 32 + 8 * cp;
;         const float sc = 0.125f * __expf((float)(63 - m) * lg);
;         float o1[8], o2[8];
; #pragma unroll
;         for (int j = 0; j < 8; ++j) { const float cs = cp_[j], sn = sp_[j]; o1[j] = (x1[j] * cs - x2[j] * sn) * sc; o2[j] = (x2[j] * cs + x1[j] * sn) * sc; }
;         *(LAS u32x4*)(kT + m * LD + 8 * cp) = pack8(o1); *(LAS u32x4*)(kT + m * LD + 32 + 8 * cp) = pack8(o2); }
;     w_store_vT(vT, proj + (size_t)row0 * NIN + C_RV + 64 * h, lane);
	v_pk_mul_f32 v[38:39], v[30:31], v[42:43]
	v_pk_mul_f32 v[30:31], v[30:31], v[44:45]
	v_pk_fma_f32 v[38:39], v[26:27], v[44:45], v[38:39]
	v_pk_fma_f32 v[26:27], v[26:27], v[42:43], v[30:31] neg_lo:[0,0,1] neg_hi:[0,0,1]
	v_pk_mul_f32 v[30:31], v[32:33], v[10:11]
	v_pk_mul_f32 v[26:27], v[12:13], v[26:27] op_sel_hi:[0,1]
	v_pk_fma_f32 v[30:31], v[28:29], v[6:7], v[30:31]
	v_pk_mul_f32 v[6:7], v[32:33], v[6:7]
	v_pk_mul_f32 v[38:39], v[12:13], v[38:39] op_sel_hi:[0,1]
	v_pk_fma_f32 v[6:7], v[28:29], v[10:11], v[6:7] neg_lo:[0,0,1] neg_hi:[0,0,1]
	v_pk_mul_f32 v[30:31], v[12:13], v[30:31] op_sel_hi:[0,1]
	v_pk_mul_f32 v[10:11], v[12:13], v[6:7] op_sel_hi:[0,1]
	v_cvt_pk_bf16_f32 v6, v16, v17
	v_cvt_pk_bf16_f32 v7, v8, v9
	v_cvt_pk_bf16_f32 v8, v26, v27
	v_cvt_pk_bf16_f32 v9, v10, v11
	v_add_u32_e32 v12, 32, v36
	ds_write_b128 v18, v[6:9] offset:11520
	v_cvt_pk_bf16_f32 v7, v4, v5
	v_add_u32_e32 v4, s35, v12
	v_mad_i64_i32 v[4:5], s[40:41], v4, s72, v[22:23]
	v_add_lshl_u32 v12, v12, s38, 5
	v_cvt_pk_bf16_f32 v6, v14, v15
	v_cvt_pk_bf16_f32 v8, v38, v39
	v_cvt_pk_bf16_f32 v9, v30, v31
	v_lshl_add_u64 v[4:5], v[4:5], 0, s[24:25]
	v_ashrrev_i32_e32 v13, 31, v12
	ds_write_b128 v18, v[6:9] offset:11584
	v_lshl_add_u64 v[4:5], v[4:5], 0, v[2:3]
	v_lshlrev_b64 v[12:13], 2, v[12:13]
	v_mov_b64_e32 v[8:9], v[108:109]
	v_mov_b64_e32 v[10:11], v[110:111]
	s_nop 0
	v_mov_b64_e32 v[4:5], v[112:113]
	v_mov_b64_e32 v[6:7], v[114:115]
	v_lshl_add_u64 v[38:39], v[0:1], 0, v[12:13]
	v_lshl_add_u64 v[40:41], v[20:21], 0, v[12:13]
	global_load_dwordx4 v[26:29], v[38:39], off
	global_load_dwordx4 v[30:33], v[40:41], off
	global_load_dwordx4 v[178:181], v[38:39], off offset:16
	global_load_dwordx4 v[182:185], v[40:41], off offset:16
	v_sub_u32_e32 v12, 31, v36
	v_cvt_f32_i32_e32 v12, v12
	v_mul_f32_e32 v12, v35, v12
	v_mul_f32_e32 v12, 0x3fb8aa3b, v12
	v_exp_f32_e32 v12, v12
	s_waitcnt vmcnt(0) lgkmcnt(0)
	v_lshlrev_b32_e32 v16, 16, v8
	v_and_b32_e32 v17, 0xffff0000, v8
	v_lshlrev_b32_e32 v42, 16, v4
	v_and_b32_e32 v43, 0xffff0000, v4
	v_pk_mul_f32 v[14:15], v[30:31], v[16:17]
	v_pk_mul_f32 v[30:31], v[30:31], v[42:43]
	v_lshlrev_b32_e32 v8, 16, v9
	v_and_b32_e32 v9, 0xffff0000, v9
	v_pk_fma_f32 v[14:15], v[26:27], v[42:43], v[14:15]
	v_pk_fma_f32 v[16:17], v[26:27], v[16:17], v[30:31] neg_lo:[0,0,1] neg_hi:[0,0,1]
	v_lshlrev_b32_e32 v26, 16, v5
	v_and_b32_e32 v27, 0xffff0000, v5
	v_pk_mul_f32 v[4:5], v[32:33], v[8:9]
	v_lshlrev_b32_e32 v42, 16, v10
	v_pk_fma_f32 v[4:5], v[28:29], v[26:27], v[4:5]
	v_pk_mul_f32 v[26:27], v[32:33], v[26:27]
	v_and_b32_e32 v43, 0xffff0000, v10
	v_pk_fma_f32 v[8:9], v[28:29], v[8:9], v[26:27] neg_lo:[0,0,1] neg_hi:[0,0,1]
	v_mov_b64_e32 v[26:27], v[178:179]
	v_mov_b64_e32 v[28:29], v[180:181]
	v_mov_b64_e32 v[30:31], v[182:183]
	v_mov_b64_e32 v[32:33], v[184:185]
	v_lshlrev_b32_e32 v44, 16, v6
	v_and_b32_e32 v45, 0xffff0000, v6
	v_lshlrev_b32_e32 v10, 16, v11
	v_and_b32_e32 v11, 0xffff0000, v11
	v_lshlrev_b32_e32 v6, 16, v7
	v_and_b32_e32 v7, 0xffff0000, v7
	v_mul_f32_e32 v12, 0x3e000000, v12
	v_pk_mul_f32 v[16:17], v[12:13], v[16:17] op_sel_hi:[0,1]
	v_pk_mul_f32 v[8:9], v[12:13], v[8:9] op_sel_hi:[0,1]
	v_pk_mul_f32 v[14:15], v[12:13], v[14:15] op_sel_hi:[0,1]
	v_pk_mul_f32 v[4:5], v[12:13], v[4:5] op_sel_hi:[0,1]
	s_waitcnt vmcnt(0) lgkmcnt(0)
	v_pk_mul_f32 v[38:39], v[30:31], v[42:43]
	v_pk_mul_f32 v[30:31], v[30:31], v[44:45]
	v_pk_fma_f32 v[38:39], v[26:27], v[44:45], v[38:39]
	v_pk_fma_f32 v[26:27], v[26:27], v[42:43], v[30:31] neg_lo:[0,0,1] neg_hi:[0,0,1]
	v_pk_mul_f32 v[30:31], v[32:33], v[10:11]
	v_pk_mul_f32 v[26:27], v[12:13], v[26:27] op_sel_hi:[0,1]
	v_pk_fma_f32 v[30:31], v[28:29], v[6:7], v[30:31]
	v_pk_mul_f32 v[6:7], v[32:33], v[6:7]
	v_pk_mul_f32 v[38:39], v[12:13], v[38:39] op_sel_hi:[0,1]
	v_pk_fma_f32 v[6:7], v[28:29], v[10:11], v[6:7] neg_lo:[0,0,1] neg_hi:[0,0,1]
	v_pk_mul_f32 v[30:31], v[12:13], v[30:31] op_sel_hi:[0,1]
	v_pk_mul_f32 v[10:11], v[12:13], v[6:7] op_sel_hi:[0,1]
	v_cvt_pk_bf16_f32 v6, v16, v17
	v_cvt_pk_bf16_f32 v7, v8, v9
	v_cvt_pk_bf16_f32 v8, v26, v27
	v_cvt_pk_bf16_f32 v9, v10, v11
	v_add_u32_e32 v12, 48, v36
	ds_write_b128 v18, v[6:9] offset:13824
	v_cvt_pk_bf16_f32 v7, v4, v5
	v_add_u32_e32 v4, s35, v12
	v_mad_i64_i32 v[4:5], s[40:41], v4, s72, v[22:23]
	v_add_lshl_u32 v12, v12, s38, 5
	v_cvt_pk_bf16_f32 v6, v14, v15
	v_cvt_pk_bf16_f32 v8, v38, v39
	v_cvt_pk_bf16_f32 v9, v30, v31
	v_lshl_add_u64 v[4:5], v[4:5], 0, s[24:25]
	v_ashrrev_i32_e32 v13, 31, v12
	ds_write_b128 v18, v[6:9] offset:13888
	v_lshl_add_u64 v[4:5], v[4:5], 0, v[2:3]
	v_lshlrev_b64 v[12:13], 2, v[12:13]
	v_mov_b64_e32 v[8:9], v[116:117]
	v_mov_b64_e32 v[10:11], v[118:119]
	s_nop 0
	v_mov_b64_e32 v[4:5], v[120:121]
	v_mov_b64_e32 v[6:7], v[122:123]
	v_lshl_add_u64 v[26:27], v[0:1], 0, v[12:13]
	v_lshl_add_u64 v[28:29], v[20:21], 0, v[12:13]
	global_load_dwordx4 v[14:17], v[26:27], off
	global_load_dwordx4 v[20:23], v[28:29], off
	global_load_dwordx4 v[178:181], v[26:27], off offset:16
	global_load_dwordx4 v[182:185], v[28:29], off offset:16
	v_sub_u32_e32 v0, 15, v36
	v_cvt_f32_i32_e32 v0, v0
	s_mul_hi_i32 s38, s35, 0x1800
	s_mulk_i32 s35, 0x1800
	s_add_u32 s35, s8, s35
	v_mul_f32_e32 v0, v35, v0
	v_mul_f32_e32 v0, 0x3fb8aa3b, v0
	v_exp_f32_e32 v0, v0
	s_addc_u32 s39, s9, s38
	s_add_u32 s38, s35, s24
	s_addc_u32 s39, s39, 0
	v_mul_f32_e32 v0, 0x3e000000, v0
	s_lshl_b32 s21, s21, 9
	s_lshl_b32 s24, s27, 2
	s_add_i32 s24, s24, s21
	s_or_b32 s34, s34, s24
	s_ashr_i32 s35, s34, 31
	s_lshl_b64 s[34:35], s[34:35], 13
	s_add_u32 s34, s67, s34
	s_addc_u32 s35, s28, s35
	s_waitcnt vmcnt(0) lgkmcnt(0)
; #define LAS __attribute__((address_space(3)))
; __device__ __forceinline__ unsigned pk2(float lo, float hi) { const f32x2_t v = {lo, hi}; const bf16x2_t b = __builtin_convertvector(v, bf16x2_t); return __builtin_bit_cast(unsigned, b); }
; __device__ __forceinline__ u32x4 pack8(const float (&v)[8]) { u32x4 w; w.x = pk2(v[0], v[1]); w.y = pk2(v[2], v[3]); w.z = pk2(v[4], v[5]); w.w = pk2(v[6], v[7]); return w; }
; #define WAVE_LDS_FENCE() asm volatile("s_waitcnt lgkmcnt(0)" ::: "memory")
; __device__ __forceinline__ void w_store_vT(LAS bf16_t* vN, const bf16_t* src, int lane) {
; #pragma unroll
;     for (int i = 0; i < 8; ++i) { const int m = (lane >> 3) + 8 * i, e0 = 8 * (lane & 7); *(LAS u32x4*)(vN + m * LD + e0) = *(const u32x4*)(src + (size_t)m * NIN + e0); }
; }
; __device__ __forceinline__ void w_kv(const LAS bf16_t* vN, const LAS bf16_t* kN, bf16_t* S, int lo, int fq) {
; #pragma unroll
;     for (int db = 0; db < 4; ++db) {
;         bf16x8 kf[2];
; #pragma unroll
;         for (int kk = 0; kk < 2; ++kk) kf[kk] = tr_frag(kN, 32 * kk + 8 * fq, 32 * kk + 8 * fq + 4, 16 * db, lo);
; #pragma unroll
;         for (int eb = 0; eb < 4; ++eb) { f32x4 acc = {0.f, 0.f, 0.f, 0.f};
; #pragma unroll
;             for (int kk = 0; kk < 2; ++kk) { const bf16x8 vf = tr_frag(vN, 32 * kk + 8 * fq, 32 * kk + 8 * fq + 4, 16 * eb, lo); acc = __builtin_amdgcn_mfma_f32_16x16x32_bf16(kf[kk], vf, acc, 0, 0, 0); }
;             *(unsigned long long*)(S + (16 * eb + lo) * 64 + 16 * db + 4 * fq) = (unsigned long long)pk2(acc[0], acc[1]) | ((unsigned long long)pk2(acc[2], acc[3]) << 32); }
;     }
; }
; __device__ __forceinline__ void w_ret_m1(unsigned char* ws, const bf16_t* proj, LAS unsigned char* wl, int b, int ck_, int h, int lane) {
;     ...
;         *(LAS u32x4*)(kT + m * LD + 8 * cp) = pack8(o1); *(LAS u32x4*)(kT + m * LD + 32 + 8 * cp) = pack8(o2); }
;     w_store_vT(vT, proj + (size_t)row0 * NIN + C_RV + 64 * h, lane);
;     WAVE_LDS_FENCE();
;     w_kv(vT, kT, (bf16_t*)(ws + WS_SRET) + (size_t)((b * NCH + ck_) * 4 + h) * 4096, lo, fq);
	v_lshlrev_b32_e32 v30, 16, v8
	v_and_b32_e32 v31, 0xffff0000, v8
	v_lshlrev_b32_e32 v32, 16, v4
	v_and_b32_e32 v33, 0xffff0000, v4
	v_pk_mul_f32 v[12:13], v[20:21], v[30:31]
	v_pk_mul_f32 v[20:21], v[20:21], v[32:33]
	v_lshlrev_b32_e32 v8, 16, v9
	v_and_b32_e32 v9, 0xffff0000, v9
	v_pk_fma_f32 v[12:13], v[14:15], v[32:33], v[12:13]
	v_pk_fma_f32 v[14:15], v[14:15], v[30:31], v[20:21] neg_lo:[0,0,1] neg_hi:[0,0,1]
	v_lshlrev_b32_e32 v20, 16, v5
	v_and_b32_e32 v21, 0xffff0000, v5
	v_pk_mul_f32 v[4:5], v[22:23], v[8:9]
	v_lshlrev_b32_e32 v30, 16, v6
	v_pk_fma_f32 v[4:5], v[16:17], v[20:21], v[4:5]
	v_pk_mul_f32 v[20:21], v[22:23], v[20:21]
	v_and_b32_e32 v31, 0xffff0000, v6
	v_pk_fma_f32 v[8:9], v[16:17], v[8:9], v[20:21] neg_lo:[0,0,1] neg_hi:[0,0,1]
	v_mov_b64_e32 v[20:21], v[178:179]
	v_mov_b64_e32 v[22:23], v[180:181]
	s_nop 0
	v_mov_b64_e32 v[26:27], v[182:183]
	v_mov_b64_e32 v[28:29], v[184:185]
	v_lshlrev_b32_e32 v16, 16, v10
	v_and_b32_e32 v17, 0xffff0000, v10
	v_lshlrev_b32_e32 v10, 16, v11
	v_and_b32_e32 v11, 0xffff0000, v11
	v_lshlrev_b32_e32 v6, 16, v7
	v_and_b32_e32 v7, 0xffff0000, v7
	v_pk_mul_f32 v[12:13], v[0:1], v[12:13] op_sel_hi:[0,1]
	v_pk_mul_f32 v[14:15], v[0:1], v[14:15] op_sel_hi:[0,1]
	v_pk_mul_f32 v[4:5], v[0:1], v[4:5] op_sel_hi:[0,1]
	v_pk_mul_f32 v[8:9], v[0:1], v[8:9] op_sel_hi:[0,1]
	s_waitcnt vmcnt(0) lgkmcnt(0)
	v_pk_mul_f32 v[32:33], v[26:27], v[16:17]
	v_pk_mul_f32 v[26:27], v[26:27], v[30:31]
	v_pk_fma_f32 v[32:33], v[20:21], v[30:31], v[32:33]
	v_pk_fma_f32 v[16:17], v[20:21], v[16:17], v[26:27] neg_lo:[0,0,1] neg_hi:[0,0,1]
	v_pk_mul_f32 v[20:21], v[28:29], v[10:11]
	v_pk_mul_f32 v[32:33], v[0:1], v[32:33] op_sel_hi:[0,1]
	v_pk_fma_f32 v[20:21], v[22:23], v[6:7], v[20:21]
	v_pk_mul_f32 v[6:7], v[28:29], v[6:7]
	v_pk_mul_f32 v[16:17], v[0:1], v[16:17] op_sel_hi:[0,1]
	v_pk_fma_f32 v[6:7], v[22:23], v[10:11], v[6:7] neg_lo:[0,0,1] neg_hi:[0,0,1]
	v_pk_mul_f32 v[20:21], v[0:1], v[20:21] op_sel_hi:[0,1]
	v_pk_mul_f32 v[0:1], v[0:1], v[6:7] op_sel_hi:[0,1]
	v_cvt_pk_bf16_f32 v6, v14, v15
	v_cvt_pk_bf16_f32 v7, v8, v9
	v_cvt_pk_bf16_f32 v8, v16, v17
	v_cvt_pk_bf16_f32 v9, v0, v1
	v_lshlrev_b32_e32 v0, 4, v25
	ds_write_b128 v18, v[6:9] offset:16128
	v_cvt_pk_bf16_f32 v6, v12, v13
	v_cvt_pk_bf16_f32 v7, v4, v5
	v_cvt_pk_bf16_f32 v8, v32, v33
	v_cvt_pk_bf16_f32 v9, v20, v21
	v_and_b32_e32 v2, 0x70, v0
	ds_write_b128 v18, v[6:9] offset:16192
	v_ashrrev_i32_e32 v9, 3, v25
	v_lshl_add_u64 v[0:1], s[38:39], 0, v[2:3]
	v_mad_i64_i32 v[4:5], s[38:39], v9, s72, v[0:1]
	global_load_dwordx4 v[224:227], v[4:5], off offset:3072
	v_add_u32_e32 v4, 8, v9
	v_mad_i64_i32 v[4:5], s[38:39], v4, s72, v[0:1]
	global_load_dwordx4 v[228:231], v[4:5], off offset:3072
	v_add_u32_e32 v4, 16, v9
	v_mad_i64_i32 v[4:5], s[38:39], v4, s72, v[0:1]
	global_load_dwordx4 v[232:235], v[4:5], off offset:3072
	v_add_u32_e32 v4, 24, v9
	v_mad_i64_i32 v[4:5], s[38:39], v4, s72, v[0:1]
	global_load_dwordx4 v[236:239], v[4:5], off offset:3072
	v_add_u32_e32 v4, 32, v9
	v_mad_i64_i32 v[4:5], s[38:39], v4, s72, v[0:1]
	global_load_dwordx4 v[240:243], v[4:5], off offset:3072
	v_add_u32_e32 v4, 40, v9
	v_mad_i64_i32 v[4:5], s[38:39], v4, s72, v[0:1]
	global_load_dwordx4 v[244:247], v[4:5], off offset:3072
	v_add_u32_e32 v4, 48, v9
	v_mad_i64_i32 v[4:5], s[38:39], v4, s72, v[0:1]
	global_load_dwordx4 v[248:251], v[4:5], off offset:3072
	v_add_u32_e32 v4, 56, v9
	v_mad_i64_i32 v[0:1], s[38:39], v4, s72, v[0:1]
	global_load_dwordx4 v[186:189], v[0:1], off offset:3072
	v_mul_lo_u32 v10, v9, s23
	v_add3_u32 v2, s6, v2, v10
	v_ashrrev_i32_e32 v8, 4, v25
	v_and_b32_e32 v17, 15, v25
	v_lshlrev_b32_e32 v0, 2, v8
	v_ashrrev_i32_e32 v1, 31, v0
	v_lshl_add_u64 v[0:1], v[0:1], 1, s[34:35]
	v_lshl_add_u64 v[26:27], v[0:1], 0, 32
	s_mov_b64 s[34:35], 0x60
	s_waitcnt vmcnt(0) lgkmcnt(0)
	ds_write_b128 v2, v[224:227]
	ds_write_b128 v2, v[228:231] offset:1152
	ds_write_b128 v2, v[232:235] offset:2304
	ds_write_b128 v2, v[236:239] offset:3456
	ds_write_b128 v2, v[240:243] offset:4608
	ds_write_b128 v2, v[244:247] offset:5760
	ds_write_b128 v2, v[248:251] offset:6912
	ds_write_b128 v2, v[186:189] offset:8064
	v_bfe_u32 v2, v25, 2, 2
	v_lshl_or_b32 v2, v8, 3, v2
	v_mul_lo_u32 v2, v2, s23
	s_waitcnt lgkmcnt(0)
	v_add3_u32 v16, s6, v34, v2
	ds_read_b64_tr_b16 v[8:9], v16 offset:9216
	ds_read_b64_tr_b16 v[10:11], v16 offset:9792
	ds_read_b64_tr_b16 v[4:5], v16 offset:13824
	ds_read_b64_tr_b16 v[6:7], v16 offset:14400
	ds_read_b64_tr_b16 v[12:13], v16
	ds_read_b64_tr_b16 v[14:15], v16 offset:576
	ds_read_b64_tr_b16 v[18:19], v16 offset:4608
	ds_read_b64_tr_b16 v[20:21], v16 offset:5184
	s_waitcnt lgkmcnt(2)
	v_mfma_f32_16x16x32_bf16 v[12:15], v[8:11], v[12:15], 0
	v_lshlrev_b32_e32 v2, 7, v17
	s_waitcnt lgkmcnt(0)
	v_mfma_f32_16x16x32_bf16 v[12:15], v[4:7], v[18:21], v[12:15]
	s_nop 7
	v_cvt_pk_bf16_f32 v18, v12, v13
	v_cvt_pk_bf16_f32 v19, v14, v15
	v_lshl_add_u64 v[12:13], v[0:1], 0, v[2:3]
	flat_store_dwordx2 v[12:13], v[18:19]
	ds_read_b64_tr_b16 v[18:19], v16 offset:32
	ds_read_b64_tr_b16 v[20:21], v16 offset:608
	ds_read_b64_tr_b16 v[22:23], v16 offset:4640
	ds_read_b64_tr_b16 v[24:25], v16 offset:5216
	s_waitcnt lgkmcnt(0)
	v_mfma_f32_16x16x32_bf16 v[18:21], v[8:11], v[18:21], 0
	v_mfma_f32_16x16x32_bf16 v[18:21], v[4:7], v[22:25], v[18:21]
	s_nop 7
	v_cvt_pk_bf16_f32 v14, v18, v19
	v_cvt_pk_bf16_f32 v15, v20, v21
	flat_store_dwordx2 v[12:13], v[14:15] offset:2048
	ds_read_b64_tr_b16 v[18:19], v16 offset:64
	ds_read_b64_tr_b16 v[20:21], v16 offset:640
	ds_read_b64_tr_b16 v[22:23], v16 offset:4672
	ds_read_b64_tr_b16 v[24:25], v16 offset:5248
	s_waitcnt lgkmcnt(0)
; #define LAS __attribute__((address_space(3)))
; __device__ __forceinline__ unsigned pk2(float lo, float hi) { const f32x2_t v = {lo, hi}; const bf16x2_t b = __builtin_convertvector(v, bf16x2_t); return __builtin_bit_cast(unsigned, b); }
; __device__ __forceinline__ void w_kv(const LAS bf16_t* vN, const LAS bf16_t* kN, bf16_t* S, int lo, int fq) {
; #pragma unroll
;     for (int db = 0; db < 4; ++db) {
;         bf16x8 kf[2];
; #pragma unroll
;         for (int kk = 0; kk < 2; ++kk) kf[kk] = tr_frag(kN, 32 * kk + 8 * fq, 32 * kk + 8 * fq + 4, 16 * db, lo);
; #pragma unroll
;         for (int eb = 0; eb < 4; ++eb) { f32x4 acc = {0.f, 0.f, 0.f, 0.f};
; #pragma unroll
;             for (int kk = 0; kk < 2; ++kk) { const bf16x8 vf = tr_frag(vN, 32 * kk + 8 * fq, 32 * kk + 8 * fq + 4, 16 * eb, lo); acc = __builtin_amdgcn_mfma_f32_16x16x32_bf16(kf[kk], vf, acc, 0, 0, 0); }
;             *(unsigned long long*)(S + (16 * eb + lo) * 64 + 16 * db + 4 * fq) = (unsigned long long)pk2(acc[0], acc[1]) | ((unsigned long long)pk2(acc[2], acc[3]) << 32); }
;     }
; }
	v_mfma_f32_16x16x32_bf16 v[18:21], v[8:11], v[18:21], 0
	v_or_b32_e32 v14, 0x1000, v2
	v_mov_b32_e32 v15, v3
	v_or_b32_e32 v2, 0x1800, v2
	v_mfma_f32_16x16x32_bf16 v[18:21], v[4:7], v[22:25], v[18:21]
	s_nop 7
	v_cvt_pk_bf16_f32 v18, v18, v19
	v_cvt_pk_bf16_f32 v19, v20, v21
	v_lshl_add_u64 v[20:21], v[0:1], 0, v[14:15]
	flat_store_dwordx2 v[20:21], v[18:19]
	ds_read_b64_tr_b16 v[18:19], v16 offset:96
	ds_read_b64_tr_b16 v[20:21], v16 offset:672
	s_waitcnt lgkmcnt(0)
	v_mfma_f32_16x16x32_bf16 v[8:11], v[8:11], v[18:21], 0
	ds_read_b64_tr_b16 v[18:19], v16 offset:4704
	ds_read_b64_tr_b16 v[20:21], v16 offset:5280
	s_waitcnt lgkmcnt(0)
	v_mfma_f32_16x16x32_bf16 v[4:7], v[4:7], v[18:21], v[8:11]
	s_nop 7
	v_cvt_pk_bf16_f32 v4, v4, v5
	v_cvt_pk_bf16_f32 v5, v6, v7
	v_lshl_add_u64 v[6:7], v[0:1], 0, v[2:3]
	flat_store_dwordx2 v[6:7], v[4:5]
	ds_read_b64_tr_b16 v[4:5], v16 offset:9248
	ds_read_b64_tr_b16 v[6:7], v16 offset:9824
	ds_read_b64_tr_b16 v[8:9], v16 offset:13856
	ds_read_b64_tr_b16 v[10:11], v16 offset:14432
	ds_read_b64_tr_b16 v[18:19], v16
	ds_read_b64_tr_b16 v[20:21], v16 offset:576
	ds_read_b64_tr_b16 v[22:23], v16 offset:4608
	ds_read_b64_tr_b16 v[24:25], v16 offset:5184
	s_waitcnt lgkmcnt(0)
	v_mfma_f32_16x16x32_bf16 v[18:21], v[4:7], v[18:21], 0
	v_mfma_f32_16x16x32_bf16 v[18:21], v[8:11], v[22:25], v[18:21]
	s_nop 7
	v_cvt_pk_bf16_f32 v18, v18, v19
	v_cvt_pk_bf16_f32 v19, v20, v21
	flat_store_dwordx2 v[12:13], v[18:19] offset:32
	ds_read_b64_tr_b16 v[18:19], v16 offset:32
	ds_read_b64_tr_b16 v[20:21], v16 offset:608
	ds_read_b64_tr_b16 v[22:23], v16 offset:4640
	ds_read_b64_tr_b16 v[24:25], v16 offset:5216
	s_waitcnt lgkmcnt(0)
	v_mfma_f32_16x16x32_bf16 v[18:21], v[4:7], v[18:21], 0
	v_mfma_f32_16x16x32_bf16 v[18:21], v[8:11], v[22:25], v[18:21]
	s_nop 7
	v_cvt_pk_bf16_f32 v18, v18, v19
	v_cvt_pk_bf16_f32 v19, v20, v21
	flat_store_dwordx2 v[12:13], v[18:19] offset:2080
	ds_read_b64_tr_b16 v[18:19], v16 offset:64
	ds_read_b64_tr_b16 v[20:21], v16 offset:640
	ds_read_b64_tr_b16 v[22:23], v16 offset:4672
	ds_read_b64_tr_b16 v[24:25], v16 offset:5248
	s_waitcnt lgkmcnt(0)
	v_mfma_f32_16x16x32_bf16 v[18:21], v[4:7], v[18:21], 0
	v_mfma_f32_16x16x32_bf16 v[18:21], v[8:11], v[22:25], v[18:21]
	s_nop 7
	v_cvt_pk_bf16_f32 v18, v18, v19
	v_cvt_pk_bf16_f32 v19, v20, v21
	v_lshl_add_u64 v[20:21], v[26:27], 0, v[14:15]
	flat_store_dwordx2 v[20:21], v[18:19]
	ds_read_b64_tr_b16 v[18:19], v16 offset:96
	ds_read_b64_tr_b16 v[20:21], v16 offset:672
	s_waitcnt lgkmcnt(0)
	v_mfma_f32_16x16x32_bf16 v[4:7], v[4:7], v[18:21], 0
	ds_read_b64_tr_b16 v[18:19], v16 offset:4704
	ds_read_b64_tr_b16 v[20:21], v16 offset:5280
	s_waitcnt lgkmcnt(0)
	v_mfma_f32_16x16x32_bf16 v[4:7], v[8:11], v[18:21], v[4:7]
	s_nop 7
	v_cvt_pk_bf16_f32 v4, v4, v5
	v_cvt_pk_bf16_f32 v5, v6, v7
	v_lshl_add_u64 v[6:7], v[26:27], 0, v[2:3]
	flat_store_dwordx2 v[6:7], v[4:5]
	ds_read_b64_tr_b16 v[4:5], v16 offset:9280
	ds_read_b64_tr_b16 v[6:7], v16 offset:9856
	ds_read_b64_tr_b16 v[8:9], v16 offset:13888
	ds_read_b64_tr_b16 v[10:11], v16 offset:14464
	ds_read_b64_tr_b16 v[18:19], v16
	ds_read_b64_tr_b16 v[20:21], v16 offset:576
	ds_read_b64_tr_b16 v[22:23], v16 offset:4608
	ds_read_b64_tr_b16 v[24:25], v16 offset:5184
	s_waitcnt lgkmcnt(0)
	v_mfma_f32_16x16x32_bf16 v[18:21], v[4:7], v[18:21], 0
	v_lshl_add_u64 v[26:27], v[0:1], 0, 64
	v_lshl_add_u64 v[0:1], v[0:1], 0, s[34:35]
	v_mfma_f32_16x16x32_bf16 v[18:21], v[8:11], v[22:25], v[18:21]
	s_nop 7
	v_cvt_pk_bf16_f32 v18, v18, v19
	v_cvt_pk_bf16_f32 v19, v20, v21
	flat_store_dwordx2 v[12:13], v[18:19] offset:64
	ds_read_b64_tr_b16 v[18:19], v16 offset:32
	ds_read_b64_tr_b16 v[20:21], v16 offset:608
	ds_read_b64_tr_b16 v[22:23], v16 offset:4640
	ds_read_b64_tr_b16 v[24:25], v16 offset:5216
	s_waitcnt lgkmcnt(0)
; #define LAS __attribute__((address_space(3)))
; __device__ __forceinline__ unsigned pk2(float lo, float hi) { const f32x2_t v = {lo, hi}; const bf16x2_t b = __builtin_convertvector(v, bf16x2_t); return __builtin_bit_cast(unsigned, b); }
; __device__ __forceinline__ void w_kv(const LAS bf16_t* vN, const LAS bf16_t* kN, bf16_t* S, int lo, int fq) {
; #pragma unroll
;     for (int db = 0; db < 4; ++db) {
;         bf16x8 kf[2];
; #pragma unroll
;         for (int kk = 0; kk < 2; ++kk) kf[kk] = tr_frag(kN, 32 * kk + 8 * fq, 32 * kk + 8 * fq + 4, 16 * db, lo);
; #pragma unroll
;         for (int eb = 0; eb < 4; ++eb) { f32x4 acc = {0.f, 0.f, 0.f, 0.f};
; #pragma unroll
;             for (int kk = 0; kk < 2; ++kk) { const bf16x8 vf = tr_frag(vN, 32 * kk + 8 * fq, 32 * kk + 8 * fq + 4, 16 * eb, lo); acc = __builtin_amdgcn_mfma_f32_16x16x32_bf16(kf[kk], vf, acc, 0, 0, 0); }
;             *(unsigned long long*)(S + (16 * eb + lo) * 64 + 16 * db + 4 * fq) = (unsigned long long)pk2(acc[0], acc[1]) | ((unsigned long long)pk2(acc[2], acc[3]) << 32); }
;     }
; }
	v_mfma_f32_16x16x32_bf16 v[18:21], v[4:7], v[18:21], 0
	v_mfma_f32_16x16x32_bf16 v[18:21], v[8:11], v[22:25], v[18:21]
	s_nop 7
	v_cvt_pk_bf16_f32 v18, v18, v19
	v_cvt_pk_bf16_f32 v19, v20, v21
	flat_store_dwordx2 v[12:13], v[18:19] offset:2112
	ds_read_b64_tr_b16 v[18:19], v16 offset:64
	ds_read_b64_tr_b16 v[20:21], v16 offset:640
	ds_read_b64_tr_b16 v[22:23], v16 offset:4672
	ds_read_b64_tr_b16 v[24:25], v16 offset:5248
	s_waitcnt lgkmcnt(0)
	v_mfma_f32_16x16x32_bf16 v[18:21], v[4:7], v[18:21], 0
	v_mfma_f32_16x16x32_bf16 v[18:21], v[8:11], v[22:25], v[18:21]
	s_nop 7
	v_cvt_pk_bf16_f32 v18, v18, v19
	v_cvt_pk_bf16_f32 v19, v20, v21
	v_lshl_add_u64 v[20:21], v[26:27], 0, v[14:15]
	flat_store_dwordx2 v[20:21], v[18:19]
	ds_read_b64_tr_b16 v[18:19], v16 offset:96
	ds_read_b64_tr_b16 v[20:21], v16 offset:672
	s_waitcnt lgkmcnt(0)
	v_mfma_f32_16x16x32_bf16 v[4:7], v[4:7], v[18:21], 0
	ds_read_b64_tr_b16 v[18:19], v16 offset:4704
	ds_read_b64_tr_b16 v[20:21], v16 offset:5280
	v_lshl_add_u64 v[14:15], v[0:1], 0, v[14:15]
	v_lshl_add_u64 v[0:1], v[0:1], 0, v[2:3]
	s_waitcnt lgkmcnt(0)
	v_mfma_f32_16x16x32_bf16 v[4:7], v[8:11], v[18:21], v[4:7]
	s_nop 7
	v_cvt_pk_bf16_f32 v4, v4, v5
	v_cvt_pk_bf16_f32 v5, v6, v7
	v_lshl_add_u64 v[6:7], v[26:27], 0, v[2:3]
	flat_store_dwordx2 v[6:7], v[4:5]
	ds_read_b64_tr_b16 v[4:5], v16 offset:9312
	ds_read_b64_tr_b16 v[6:7], v16 offset:9888
	ds_read_b64_tr_b16 v[8:9], v16 offset:13920
	ds_read_b64_tr_b16 v[10:11], v16 offset:14496
	ds_read_b64_tr_b16 v[18:19], v16
	ds_read_b64_tr_b16 v[20:21], v16 offset:576
	ds_read_b64_tr_b16 v[22:23], v16 offset:4608
	ds_read_b64_tr_b16 v[24:25], v16 offset:5184
	s_waitcnt lgkmcnt(0)
	v_mfma_f32_16x16x32_bf16 v[18:21], v[4:7], v[18:21], 0
	v_mfma_f32_16x16x32_bf16 v[18:21], v[8:11], v[22:25], v[18:21]
	s_nop 7
	v_cvt_pk_bf16_f32 v18, v18, v19
	v_cvt_pk_bf16_f32 v19, v20, v21
	flat_store_dwordx2 v[12:13], v[18:19] offset:96
	ds_read_b64_tr_b16 v[18:19], v16 offset:32
	ds_read_b64_tr_b16 v[20:21], v16 offset:608
	ds_read_b64_tr_b16 v[22:23], v16 offset:4640
	ds_read_b64_tr_b16 v[24:25], v16 offset:5216
	s_waitcnt lgkmcnt(0)
	v_mfma_f32_16x16x32_bf16 v[18:21], v[4:7], v[18:21], 0
	v_mfma_f32_16x16x32_bf16 v[18:21], v[8:11], v[22:25], v[18:21]
	s_nop 7
	v_cvt_pk_bf16_f32 v18, v18, v19
	v_cvt_pk_bf16_f32 v19, v20, v21
	flat_store_dwordx2 v[12:13], v[18:19] offset:2144
	ds_read_b64_tr_b16 v[18:19], v16 offset:64
	ds_read_b64_tr_b16 v[20:21], v16 offset:640
	ds_read_b64_tr_b16 v[22:23], v16 offset:4672
	ds_read_b64_tr_b16 v[24:25], v16 offset:5248
	s_waitcnt lgkmcnt(0)
	v_mfma_f32_16x16x32_bf16 v[18:21], v[4:7], v[18:21], 0
	v_mfma_f32_16x16x32_bf16 v[18:21], v[8:11], v[22:25], v[18:21]
	s_nop 7
	v_cvt_pk_bf16_f32 v12, v18, v19
	v_cvt_pk_bf16_f32 v13, v20, v21
	flat_store_dwordx2 v[14:15], v[12:13]
	ds_read_b64_tr_b16 v[12:13], v16 offset:96
	ds_read_b64_tr_b16 v[14:15], v16 offset:672
	s_waitcnt lgkmcnt(0)
	v_mfma_f32_16x16x32_bf16 v[4:7], v[4:7], v[12:15], 0
	ds_read_b64_tr_b16 v[12:13], v16 offset:4704
	ds_read_b64_tr_b16 v[14:15], v16 offset:5280
	s_waitcnt lgkmcnt(0)
	v_mfma_f32_16x16x32_bf16 v[4:7], v[8:11], v[12:15], v[4:7]
	s_nop 7
	v_cvt_pk_bf16_f32 v4, v4, v5
	v_cvt_pk_bf16_f32 v5, v6, v7
	flat_store_dwordx2 v[0:1], v[4:5]
	s_waitcnt lgkmcnt(0)
	s_branch .LBB0_515
